# attention loop as v8 plus one static s_setprio 1 for waves 4-7 during the attention loop
# speedup vs baseline: 1.0020x; 1.0020x over previous
; __device__ __forceinline__ int v_st(int k, int c) { const int kk = (k & ~0xC) | ((k & 4) << 1) | ((k & 8) >> 1); return ((kk >> 3) * 4 + (c >> 5)) * 512 + ((kk & 7) * 32 + (c & 31)) * 2; }
; __device__ __forceinline__ void attn_unit(const bf16* __restrict__ Qb, const bf16* __restrict__ KN, const bf16* __restrict__ KR, ...
;     ...
;     const float rsn = 1.0f / sqrtf(ssn * (1.0f / 128) + 1e-6f), rsr = 1.0f / sqrtf(ssr * (1.0f / 64) + 1e-6f);
; #pragma unroll
;     for (int d0 = 0; d0 < 8; ++d0) { u32x4 w;
; #pragma unroll
;       for (int e2 = 0; e2 < 4; ++e2) { const int d = d0 * 16 + hi * 8 + 2 * e2;
;         const float v0 = __builtin_bit_cast(float, ((unsigned)(unsigned short)raw[d0][2 * e2]) << 16) * rsn * qn_g[d], v1 = __builtin_bit_cast(float, ((unsigned)(unsigned short)raw[d0][2 * e2 + 1]) << 16) * rsn * qn_g[d + 1];
;         w[e2] = cvtpk(v0, v1); }
;       qr[d0] = *reinterpret_cast<bf16x8*>(&w); }
;     const int npos = npos0 < 0 ? -1 : npos0 + wid * QBLK + r32;
; #pragma unroll
;     for (int a = 0; a < 2; ++a) { u32x4 w0, w1; const int pos = a ? (npos & 63) : (npos >> 6);
; #pragma unroll
;       for (int e2 = 0; e2 < 4; ++e2) { float o0[2], o1[2];
; #pragma unroll
;         for (int t = 0; t < 2; ++t) { const int e = 2 * e2 + t, f = hi * 8 + e;
;           const float x0 = __builtin_bit_cast(float, ((unsigned)(unsigned short)raw[8 + 2 * a][e]) << 16) * rsr * qr_g[a * 32 + f];
;           const float x1 = __builtin_bit_cast(float, ((unsigned)(unsigned short)raw[9 + 2 * a][e]) << 16) * rsr * qr_g[a * 32 + 16 + f];
;           float c = 1.f, sn = 0.f; if (npos >= 0) { c = rope[(pos * 16 + f) * 2]; sn = rope[(pos * 16 + f) * 2 + 1]; }
;           o0[t] = x0 * c - x1 * sn; o1[t] = x1 * c + x0 * sn; }
;         w0[e2] = cvtpk(o0[0], o0[1]); w1[e2] = cvtpk(o1[0], o1[1]); }
;       qs[(2 * a) * 64] = *reinterpret_cast<bf16x8*>(&w0); qs[(2 * a + 1) * 64] = *reinterpret_cast<bf16x8*>(&w1); }
;   }
;   int kb[4];
; #pragma unroll
;   for (int j = 0; j < 4; ++j) kb[j] = r32 * 384 + ((j * 32 + hi * 16) ^ (((r32 >> 1) & 7) << 4));
;   const int sr = tid >> 4, sc = (tid & 15) * 8, vst0 = v_st(sr, sc), vst1 = v_st(32 + sr, sc);
;   const int knd0 = KSWZ(sr, sc * 2), knd1 = knd0 + 32 * 384, krd = KSWZ(tid >> 3, (16 + (tid & 7)) * 16);
;   const int vb0 = (int)(uintptr_t)V_lds + v_rd_base(lane);
;   bf16x8 vs0, vs1, ks0, ks1, ks2;
.LBB0_106:
	s_or_b64 exec, exec, s[8:9]
	v_mul_f32_e32 v137, v148, v186
	v_mov_b32_e32 v149, v148
	v_mul_f32_e32 v136, v148, v185
	s_waitcnt vmcnt(2)
	v_mul_f32_e32 v137, v137, v173
	v_mul_f32_e32 v136, v136, v174
	v_mul_f32_e32 v173, v137, v143
	v_mul_f32_e32 v174, v137, v142
	v_pk_mul_f32 v[38:39], v[148:149], v[38:39]
	v_fma_f32 v173, v136, v142, -v173
	v_fmac_f32_e32 v174, v136, v143
	s_waitcnt vmcnt(0)
	v_pk_mul_f32 v[142:143], v[38:39], v[164:165]
	v_mul_f32_e32 v39, v148, v184
	v_mul_f32_e32 v38, v148, v183
	v_mul_f32_e32 v39, v39, v171
	v_mul_f32_e32 v38, v38, v172
	v_mul_f32_e32 v136, v39, v159
	v_fma_f32 v164, v38, v158, -v136
	v_mul_f32_e32 v158, v39, v158
	v_pk_mul_f32 v[36:37], v[148:149], v[36:37]
	v_fmac_f32_e32 v158, v38, v159
	v_pk_mul_f32 v[38:39], v[36:37], v[162:163]
	v_mul_f32_e32 v37, v148, v182
	v_mul_f32_e32 v36, v148, v181
	v_mul_f32_e32 v37, v37, v169
	v_mul_f32_e32 v36, v36, v170
	v_mul_f32_e32 v136, v37, v153
	v_fma_f32 v159, v36, v152, -v136
	v_mul_f32_e32 v152, v37, v152
	v_mul_f32_e32 v37, v148, v180
	v_fmac_f32_e32 v152, v36, v153
	v_mul_f32_e32 v36, v148, v179
	v_mul_f32_e32 v37, v37, v167
	v_pk_mul_f32 v[32:33], v[148:149], v[32:33]
	v_mul_f32_e32 v36, v36, v168
	v_mul_f32_e32 v136, v37, v141
	v_mul_f32_e32 v137, v37, v140
	v_pk_mul_f32 v[32:33], v[32:33], v[144:145]
	v_fma_f32 v136, v36, v140, -v136
	v_fmac_f32_e32 v137, v36, v141
	v_mul_f32_e32 v36, v33, v146
	v_pk_mul_f32 v[34:35], v[148:149], v[34:35]
	v_pk_fma_f32 v[36:37], v[32:33], v[146:147], v[36:37] op_sel:[1,0,0] op_sel_hi:[0,1,0] neg_lo:[1,0,0] neg_hi:[1,0,0]
	v_pk_mul_f32 v[34:35], v[34:35], v[156:157]
	v_mul_f32_e32 v36, v32, v146
	v_pk_fma_f32 v[32:33], v[32:33], v[146:147], v[36:37] op_sel_hi:[1,1,0]
	v_cvt_pk_bf16_f32 v36, v136, v37
	v_mul_f32_e32 v136, v35, v150
	v_cvt_pk_bf16_f32 v32, v137, v33
	v_pk_fma_f32 v[136:137], v[34:35], v[150:151], v[136:137] op_sel:[1,0,0] op_sel_hi:[0,1,0] neg_lo:[1,0,0] neg_hi:[1,0,0]
	v_mul_f32_e32 v136, v34, v150
	v_pk_fma_f32 v[34:35], v[34:35], v[150:151], v[136:137] op_sel_hi:[1,1,0]
	v_cvt_pk_bf16_f32 v37, v159, v137
	v_mul_f32_e32 v34, v39, v154
	v_cvt_pk_bf16_f32 v33, v152, v35
	v_pk_fma_f32 v[34:35], v[38:39], v[154:155], v[34:35] op_sel:[1,0,0] op_sel_hi:[0,1,0] neg_lo:[1,0,0] neg_hi:[1,0,0]
	v_mul_f32_e32 v34, v38, v154
	v_pk_fma_f32 v[38:39], v[38:39], v[154:155], v[34:35] op_sel_hi:[1,1,0]
	s_waitcnt lgkmcnt(2)
	v_add_f32_e32 v34, v188, v189
	v_fmamk_f32 v34, v34, 0x3c000000, v243
	v_mul_f32_e32 v38, 0x4f800000, v34
	v_cmp_gt_f32_e32 vcc, s71, v34
	s_lshl_b32 s2, s39, 9
	v_ashrrev_i32_e32 v162, 4, v178
	v_cndmask_b32_e32 v136, v34, v38, vcc
	v_sqrt_f32_e32 v137, v136
	v_cvt_pk_bf16_f32 v38, v164, v35
	v_cvt_pk_bf16_f32 v34, v158, v39
	v_ashrrev_i32_e32 v163, 31, v162
	v_add_u32_e32 v35, -1, v137
	v_fma_f32 v39, -v35, v137, v136
	v_cmp_ge_f32_e64 s[6:7], 0, v39
	v_add_u32_e32 v39, 1, v137
	v_lshlrev_b32_e32 v158, 3, v178
	v_cndmask_b32_e64 v35, v137, v35, s[6:7]
	v_fma_f32 v137, -v39, v137, v136
	v_cmp_lt_f32_e64 s[6:7], 0, v137
	v_mov_b32_e32 v137, v209
	v_ashrrev_i32_e32 v159, 31, v158
	v_cndmask_b32_e64 v35, v35, v39, s[6:7]
	v_mul_f32_e32 v39, 0x37800000, v35
	v_cndmask_b32_e32 v35, v35, v39, vcc
	v_cmp_class_f32_e32 vcc, v136, v244
	s_mov_b32 s8, 0
	s_mov_b32 s9, s8
	v_cndmask_b32_e32 v35, v35, v136, vcc
	v_div_scale_f32 v39, s[0:1], v35, v35, 1.0
	v_readlane_b32 s0, v254, 20
	v_rcp_f32_e32 v164, v39
	v_readlane_b32 s1, v254, 21
	s_add_u32 s46, s0, s2
	s_addc_u32 s47, s1, 0
	s_add_i32 s0, 0, 0x1e000
	s_cmp_lg_u32 0, -1
	s_cselect_b32 s1, 0, 0
	s_ashr_i32 s11, s10, 31
	v_fma_f32 v136, -v39, v164, 1.0
	v_lshl_add_u64 v[140:141], v[162:163], 0, s[10:11]
	v_fmac_f32_e32 v164, v136, v164
	v_and_b32_e32 v136, 0x78, v158
	v_lshlrev_b64 v[140:141], 11, v[140:141]
	v_lshlrev_b32_e32 v136, 1, v136
	v_lshl_add_u64 v[140:141], s[46:47], 0, v[140:141]
	v_lshl_add_u64 v[140:141], v[140:141], 0, v[136:137]
	s_lshl_b64 s[2:3], s[10:11], 7
	v_add_co_u32_e64 v144, s[6:7], s73, v140
	s_add_u32 s2, s26, s2
	s_nop 0
	v_addc_co_u32_e64 v145, s[6:7], 0, v141, s[6:7]
	global_load_dwordx4 v[146:149], v[140:141], off
	global_load_dwordx4 v[150:153], v[140:141], off offset:256
	global_load_dwordx4 v[154:157], v[144:145], off
	global_load_dwordx4 v[168:171], v[144:145], off offset:256
	s_addc_u32 s3, s27, s3
	v_lshlrev_b64 v[140:141], 1, v[158:159]
	v_lshl_add_u64 v[144:145], s[2:3], 0, v[140:141]
	global_load_dwordx4 v[182:185], v[144:145], off
	v_div_scale_f32 v165, vcc, 1.0, v35, 1.0
	v_mul_f32_e32 v144, v165, v164
	v_fma_f32 v145, -v39, v144, v165
	v_fmac_f32_e32 v144, v145, v164
	v_fma_f32 v39, -v39, v144, v165
	v_div_fmas_f32 v39, v39, v164, v144
	v_div_fixup_f32 v144, v39, v35, 1.0
	v_pk_mul_f32 v[96:97], v[144:145], v[96:97] op_sel_hi:[0,1]
	v_pk_mul_f32 v[28:29], v[28:29], v[96:97]
	s_movk_i32 s2, 0x180
	v_cvt_pk_bf16_f32 v96, v28, v29
	v_pk_mul_f32 v[28:29], v[144:145], v[134:135] op_sel_hi:[0,1]
	v_pk_mul_f32 v[28:29], v[30:31], v[28:29]
	s_sub_i32 s45, s12, s42
	v_cvt_pk_bf16_f32 v97, v28, v29
	v_pk_mul_f32 v[28:29], v[144:145], v[98:99] op_sel_hi:[0,1]
	v_pk_mul_f32 v[24:25], v[24:25], v[28:29]
	s_mov_b32 s10, s8
	v_cvt_pk_bf16_f32 v98, v24, v25
	v_pk_mul_f32 v[24:25], v[144:145], v[104:105] op_sel_hi:[0,1]
	v_pk_mul_f32 v[24:25], v[26:27], v[24:25]
	s_mov_b32 s11, s8
	v_cvt_pk_bf16_f32 v99, v24, v25
	v_pk_mul_f32 v[24:25], v[144:145], v[100:101] op_sel_hi:[0,1]
	v_pk_mul_f32 v[20:21], v[20:21], v[24:25]
	s_mov_b32 s12, s8
	v_cvt_pk_bf16_f32 v100, v20, v21
	v_pk_mul_f32 v[20:21], v[144:145], v[102:103] op_sel_hi:[0,1]
	v_pk_mul_f32 v[20:21], v[22:23], v[20:21]
	s_mov_b32 s13, s8
	v_cvt_pk_bf16_f32 v101, v20, v21
; __device__ __forceinline__ int v_st(int k, int c) { const int kk = (k & ~0xC) | ((k & 4) << 1) | ((k & 8) >> 1); return ((kk >> 3) * 4 + (c >> 5)) * 512 + ((kk & 7) * 32 + (c & 31)) * 2; }
; __device__ __forceinline__ void qkt(f32x16& p0, f32x16& p1, const char* Ks, const bf16x8* qr, const bf16x8* qs, const int* kb) {
;     ...
;   for (int d0 = 0; d0 < 12; ++d0) { const int off = kb[d0 & 3] + (d0 >> 2) * 128;
;     bf16x8 b0 = *reinterpret_cast<const bf16x8*>(Ks + off);
;     bf16x8 b1 = *reinterpret_cast<const bf16x8*>(Ks + off + 32 * 384);
;     const bf16x8 q = d0 < 8 ? qr[d0 < 8 ? d0 : 0] : qs[(d0 - 8) * 64];
;     p0 = __builtin_amdgcn_mfma_f32_32x32x16_bf16(b0, q, p0, 0, 0, 0);
;     p1 = __builtin_amdgcn_mfma_f32_32x32x16_bf16(b1, q, p1, 0, 0, 0); }
; __device__ __forceinline__ void attn_unit(const bf16* __restrict__ Qb, const bf16* __restrict__ KN, const bf16* __restrict__ KR, ...
;     ...
;       for (int e2 = 0; e2 < 4; ++e2) { float o0[2], o1[2];
; #pragma unroll
;         for (int t = 0; t < 2; ++t) { const int e = 2 * e2 + t, f = hi * 8 + e;
;           const float x0 = __builtin_bit_cast(float, ((unsigned)(unsigned short)raw[8 + 2 * a][e]) << 16) * rsr * qr_g[a * 32 + f];
;           const float x1 = __builtin_bit_cast(float, ((unsigned)(unsigned short)raw[9 + 2 * a][e]) << 16) * rsr * qr_g[a * 32 + 16 + f];
;           float c = 1.f, sn = 0.f; if (npos >= 0) { c = rope[(pos * 16 + f) * 2]; sn = rope[(pos * 16 + f) * 2 + 1]; }
;           o0[t] = x0 * c - x1 * sn; o1[t] = x1 * c + x0 * sn; }
;         w0[e2] = cvtpk(o0[0], o0[1]); w1[e2] = cvtpk(o1[0], o1[1]); }
;       qs[(2 * a) * 64] = *reinterpret_cast<bf16x8*>(&w0); qs[(2 * a + 1) * 64] = *reinterpret_cast<bf16x8*>(&w1); }
;   }
;   int kb[4];
; #pragma unroll
;   for (int j = 0; j < 4; ++j) kb[j] = r32 * 384 + ((j * 32 + hi * 16) ^ (((r32 >> 1) & 7) << 4));
;   const int sr = tid >> 4, sc = (tid & 15) * 8, vst0 = v_st(sr, sc), vst1 = v_st(32 + sr, sc);
;   const int knd0 = KSWZ(sr, sc * 2), knd1 = knd0 + 32 * 384, krd = KSWZ(tid >> 3, (16 + (tid & 7)) * 16);
;   const int vb0 = (int)(uintptr_t)V_lds + v_rd_base(lane);
;   bf16x8 vs0, vs1, ks0, ks1, ks2;
;     ...
;   f32x16 pA0, pA1, pB0, pB1; float mnA, mnB, alA, alB; bf16x8 pa0, pa1, pa2, pa3; const int NT = seq / KVBLK;
;   SLOAD(0); SWAIT(); SWRITE(0); __syncthreads();
;   qkt(pA0, pA1, K_lds, qr, qs, kb); partialSM(pA0, pA1, m_reg, mnA, alA);
	v_pk_mul_f32 v[20:21], v[144:145], v[46:47] op_sel_hi:[0,1]
	v_pk_mul_f32 v[16:17], v[16:17], v[20:21]
	v_mul_f32_e32 v20, v143, v138
	v_pk_fma_f32 v[20:21], v[142:143], v[138:139], v[20:21] op_sel:[1,0,0] op_sel_hi:[0,1,0] neg_lo:[1,0,0] neg_hi:[1,0,0]
	v_mul_f32_e32 v20, v142, v138
	v_pk_fma_f32 v[22:23], v[142:143], v[138:139], v[20:21] op_sel_hi:[1,1,0]
	v_cvt_pk_bf16_f32 v39, v173, v21
	v_and_b32_e32 v20, 0xfffff0, v162
	v_lshlrev_b32_e32 v21, 1, v162
	v_and_or_b32 v20, v21, 8, v20
	v_cvt_pk_bf16_f32 v35, v174, v23
	v_lshrrev_b32_e32 v21, 1, v162
	v_lshrrev_b32_e32 v20, 1, v20
	v_bfe_u32 v22, v158, 5, 2
	v_and_b32_e32 v23, 3, v162
	v_or_b32_e32 v20, v20, v22
	v_and_or_b32 v21, v21, 4, v23
	v_lshlrev_b32_e32 v20, 9, v20
	v_lshlrev_b32_e32 v21, 6, v21
	v_and_b32_e32 v23, 48, v136
	v_or3_b32 v174, v20, v21, v23
	v_add_u32_e32 v20, 32, v162
	v_and_b32_e32 v24, 0xfffff0, v20
	v_lshlrev_b32_e32 v20, 1, v20
	v_and_or_b32 v20, v20, 8, v24
	v_lshrrev_b32_e32 v20, 1, v20
	v_or_b32_e32 v20, v20, v22
	v_lshlrev_b32_e32 v20, 9, v20
	v_or3_b32 v175, v20, v21, v23
	v_lshrrev_b32_e32 v21, 1, v178
	v_mul_lo_u32 v20, v162, s2
	v_and_b32_e32 v21, 0x70, v21
	v_xad_u32 v179, v136, v21, v20
	v_lshlrev_b32_e32 v21, 4, v178
	v_lshrrev_b32_e32 v20, 3, v178
	v_and_b32_e32 v21, 0x70, v21
	v_mul_u32_u24_e32 v142, 0x180, v176
	v_and_b32_e32 v143, 0x70, v158
	v_mul_lo_u32 v20, v20, s2
	v_or_b32_e32 v21, 0x100, v21
	v_and_b32_e32 v22, 0x70, v178
	ds_write_b128 v161, v[36:39] offset:2048
	ds_write_b128 v161, v[32:35] offset:3072
	v_bitop3_b32 v173, v208, v142, v143 bitop3:0xde
	v_xad_u32 v180, v21, v22, v20
	v_add_u32_e32 v145, 0, v174
	v_add_u32_e32 v158, 0, v175
	v_add_u32_e32 v20, 0, v179
	s_waitcnt vmcnt(0)
	s_waitcnt vmcnt(3)
	ds_write_b128 v145, v[150:153]
	s_waitcnt vmcnt(1)
	ds_write_b128 v158, v[168:171]
	ds_write_b128 v20, v[146:149] offset:49152
	ds_write_b128 v20, v[154:157] offset:61440
	v_add_u32_e32 v20, 0, v180
	v_add_u32_e32 v159, 0, v173
	s_waitcnt vmcnt(0)
	ds_write_b128 v20, v[182:185] offset:49152
	s_waitcnt lgkmcnt(0)
	s_barrier
	ds_read_b128 v[20:23], v159 offset:49152
	v_cvt_pk_bf16_f32 v102, v16, v17
	v_pk_mul_f32 v[16:17], v[144:145], v[44:45] op_sel_hi:[0,1]
	v_pk_mul_f32 v[16:17], v[18:19], v[16:17]
	ds_read_b128 v[32:35], v159 offset:61440
	ds_read_b128 v[146:149], v159 offset:49280
	v_cvt_pk_bf16_f32 v103, v16, v17
	v_pk_mul_f32 v[16:17], v[144:145], v[42:43] op_sel_hi:[0,1]
	v_pk_mul_f32 v[36:37], v[76:77], v[16:17]
	s_waitcnt lgkmcnt(2)
	v_mfma_f32_32x32x16_bf16 v[16:31], v[20:23], v[96:99], 0
	v_cvt_pk_bf16_f32 v104, v36, v37
	v_or_b32_e32 v36, 32, v208
	v_bitop3_b32 v181, v36, v142, v143 bitop3:0xde
	v_mul_f32_e64 v76, v144, v40
	v_mul_f32_e64 v77, v144, v41
	v_add_u32_e32 v164, 0, v181
	ds_read_b128 v[150:153], v164 offset:49152
	ds_read_b128 v[154:157], v159 offset:49408
	v_pk_mul_f32 v[76:77], v[78:79], v[76:77]
	s_waitcnt lgkmcnt(3)
	v_mfma_f32_32x32x16_bf16 v[32:47], v[32:35], v[96:99], 0
	v_cvt_pk_bf16_f32 v105, v76, v77
	v_mul_f32_e64 v76, v144, v106
	v_mul_f32_e64 v77, v144, v107
	v_mul_f32_e64 v72, v72, v76
	v_mul_f32_e64 v73, v73, v77
	ds_read_b128 v[76:79], v164 offset:61440
	ds_read_b128 v[168:171], v164 offset:49280
	v_cvt_pk_bf16_f32 v106, v72, v73
	v_pk_mul_f32 v[72:73], v[144:145], v[132:133] op_sel_hi:[0,1]
	v_pk_mul_f32 v[138:139], v[74:75], v[72:73]
	s_waitcnt lgkmcnt(3)
	v_mfma_f32_32x32x16_bf16 v[16:31], v[150:153], v[100:103], v[16:31]
	v_or_b32_e32 v72, 64, v208
	v_bitop3_b32 v182, v72, v142, v143 bitop3:0xde
	v_add_u32_e32 v165, 0, v182
	ds_read_b128 v[72:75], v165 offset:49152
	ds_read_b128 v[132:135], v164 offset:49408
	v_cvt_pk_bf16_f32 v107, v138, v139
	s_and_b64 s[2:3], s[4:5], exec
	s_cselect_b32 s2, s44, s45
	s_waitcnt lgkmcnt(3)
	v_mfma_f32_32x32x16_bf16 v[32:47], v[76:79], v[100:103], v[32:47]
	v_mul_f32_e64 v76, v144, v116
	v_mul_f32_e64 v77, v144, v117
	v_mul_f32_e64 v68, v68, v76
	v_mul_f32_e64 v69, v69, v77
	ds_read_b128 v[76:79], v165 offset:61440
	ds_read_b128 v[150:153], v165 offset:49280
	v_cvt_pk_bf16_f32 v116, v68, v69
	v_pk_mul_f32 v[68:69], v[144:145], v[130:131] op_sel_hi:[0,1]
	v_pk_mul_f32 v[68:69], v[70:71], v[68:69]
	s_add_i32 s2, s2, 64
	s_waitcnt lgkmcnt(3)
	v_mfma_f32_32x32x16_bf16 v[16:31], v[72:75], v[104:107], v[16:31]
	v_cvt_pk_bf16_f32 v117, v68, v69
	v_or_b32_e32 v68, 0x60, v208
	v_bitop3_b32 v183, v68, v142, v143 bitop3:0xde
	v_add_u32_e32 v130, 0, v183
	ds_read_b128 v[68:71], v130 offset:49152
	ds_read_b128 v[72:75], v165 offset:49408
	s_ashr_i32 s3, s2, 31
	s_mov_b32 s14, s8
	s_waitcnt lgkmcnt(3)
	v_mfma_f32_32x32x16_bf16 v[32:47], v[76:79], v[104:107], v[32:47]
	v_mul_f32_e64 v76, v144, v118
	v_mul_f32_e64 v77, v144, v119
	v_mul_f32_e64 v64, v64, v76
	v_mul_f32_e64 v65, v65, v77
	v_mul_f32_e64 v76, v144, v108
	v_mul_f32_e64 v77, v144, v109
	v_cvt_pk_bf16_f32 v118, v64, v65
	v_pk_mul_f32 v[64:65], v[144:145], v[128:129] op_sel_hi:[0,1]
	v_pk_mul_f32 v[64:65], v[66:67], v[64:65]
	v_pk_mul_f32 v[60:61], v[60:61], v[76:77]
	v_cvt_pk_bf16_f32 v119, v64, v65
	v_cvt_pk_bf16_f32 v108, v60, v61
	v_pk_mul_f32 v[60:61], v[144:145], v[126:127] op_sel_hi:[0,1]
	s_waitcnt lgkmcnt(1)
	v_mfma_f32_32x32x16_bf16 v[16:31], v[68:71], v[116:119], v[16:31]
	ds_read_b128 v[68:71], v130 offset:61440
	v_mul_f32_e64 v76, v62, v60
	v_mul_f32_e64 v77, v63, v61
	ds_read_b128 v[64:67], v130 offset:49280
	ds_read_b128 v[60:63], v130 offset:49408
	v_cvt_pk_bf16_f32 v109, v76, v77
	s_mov_b32 s15, s8
	s_mov_b32 s16, s8
	s_waitcnt lgkmcnt(2)
; __device__ __forceinline__ void attn_unit(const bf16* __restrict__ Qb, const bf16* __restrict__ KN, const bf16* __restrict__ KR, ...
;     ...
;     for (int d0 = 0; d0 < 8; ++d0) { u32x4 w;
; #pragma unroll
;       for (int e2 = 0; e2 < 4; ++e2) { const int d = d0 * 16 + hi * 8 + 2 * e2;
;         const float v0 = __builtin_bit_cast(float, ((unsigned)(unsigned short)raw[d0][2 * e2]) << 16) * rsn * qn_g[d], v1 = __builtin_bit_cast(float, ((unsigned)(unsigned short)raw[d0][2 * e2 + 1]) << 16) * rsn * qn_g[d + 1];
;         w[e2] = cvtpk(v0, v1); }
;       qr[d0] = *reinterpret_cast<bf16x8*>(&w); }
;     const int npos = npos0 < 0 ? -1 : npos0 + wid * QBLK + r32;
; #pragma unroll
;     for (int a = 0; a < 2; ++a) { u32x4 w0, w1; const int pos = a ? (npos & 63) : (npos >> 6);
; #pragma unroll
;       for (int e2 = 0; e2 < 4; ++e2) { float o0[2], o1[2];
; #pragma unroll
;         for (int t = 0; t < 2; ++t) { const int e = 2 * e2 + t, f = hi * 8 + e;
;           const float x0 = __builtin_bit_cast(float, ((unsigned)(unsigned short)raw[8 + 2 * a][e]) << 16) * rsr * qr_g[a * 32 + f];
;           const float x1 = __builtin_bit_cast(float, ((unsigned)(unsigned short)raw[9 + 2 * a][e]) << 16) * rsr * qr_g[a * 32 + 16 + f];
;           float c = 1.f, sn = 0.f; if (npos >= 0) { c = rope[(pos * 16 + f) * 2]; sn = rope[(pos * 16 + f) * 2 + 1]; }
;           o0[t] = x0 * c - x1 * sn; o1[t] = x1 * c + x0 * sn; }
;         w0[e2] = cvtpk(o0[0], o0[1]); w1[e2] = cvtpk(o1[0], o1[1]); }
;       qs[(2 * a) * 64] = *reinterpret_cast<bf16x8*>(&w0); qs[(2 * a + 1) * 64] = *reinterpret_cast<bf16x8*>(&w1); }
;   }
;   int kb[4];
; #pragma unroll
;   for (int j = 0; j < 4; ++j) kb[j] = r32 * 384 + ((j * 32 + hi * 16) ^ (((r32 >> 1) & 7) << 4));
;   const int sr = tid >> 4, sc = (tid & 15) * 8, vst0 = v_st(sr, sc), vst1 = v_st(32 + sr, sc);
;   const int knd0 = KSWZ(sr, sc * 2), knd1 = knd0 + 32 * 384, krd = KSWZ(tid >> 3, (16 + (tid & 7)) * 16);
;   const int vb0 = (int)(uintptr_t)V_lds + v_rd_base(lane);
;   bf16x8 vs0, vs1, ks0, ks1, ks2;
;     ...
;   f32x16 pA0, pA1, pB0, pB1; float mnA, mnB, alA, alB; bf16x8 pa0, pa1, pa2, pa3; const int NT = seq / KVBLK;
;   SLOAD(0); SWAIT(); SWRITE(0); __syncthreads();
;   qkt(pA0, pA1, K_lds, qr, qs, kb); partialSM(pA0, pA1, m_reg, mnA, alA);
;   SLOAD(KVBLK); SWAIT(); SWRITE(1); __syncthreads();
	v_mfma_f32_32x32x16_bf16 v[32:47], v[68:71], v[116:119], v[32:47]
	v_mul_f32_e64 v68, v144, v110
	v_mul_f32_e64 v69, v144, v111
	v_mul_f32_e64 v56, v56, v68
	v_mul_f32_e64 v57, v57, v69
	v_mul_f32_e64 v68, v144, v112
	v_mul_f32_e64 v69, v144, v113
	v_cvt_pk_bf16_f32 v110, v56, v57
	v_pk_mul_f32 v[56:57], v[144:145], v[124:125] op_sel_hi:[0,1]
	v_pk_mul_f32 v[56:57], v[58:59], v[56:57]
	v_pk_mul_f32 v[52:53], v[52:53], v[68:69]
	v_cvt_pk_bf16_f32 v111, v56, v57
	ds_read_b128 v[56:59], v159 offset:61568
	v_cvt_pk_bf16_f32 v112, v52, v53
	v_pk_mul_f32 v[52:53], v[144:145], v[122:123] op_sel_hi:[0,1]
	v_pk_mul_f32 v[68:69], v[54:55], v[52:53]
	ds_read_b128 v[52:55], v159 offset:61696
	s_waitcnt lgkmcnt(1)
	v_mfma_f32_32x32x16_bf16 v[32:47], v[56:59], v[108:111], v[32:47]
	v_mul_f32_e64 v56, v144, v114
	v_mul_f32_e64 v57, v144, v115
	v_mul_f32_e64 v48, v48, v56
	v_mul_f32_e64 v49, v49, v57
	v_mul_f32_e64 v56, v144, v94
	v_mul_f32_e64 v57, v144, v95
	v_cvt_pk_bf16_f32 v114, v48, v49
	v_pk_mul_f32 v[48:49], v[144:145], v[120:121] op_sel_hi:[0,1]
	v_pk_mul_f32 v[48:49], v[50:51], v[48:49]
	v_pk_mul_f32 v[12:13], v[12:13], v[56:57]
	v_cvt_pk_bf16_f32 v115, v48, v49
	ds_read_b128 v[48:51], v164 offset:61568
	v_mfma_f32_32x32x16_bf16 v[16:31], v[146:149], v[108:111], v[16:31]
	v_cvt_pk_bf16_f32 v113, v68, v69
	v_cvt_pk_bf16_f32 v120, v12, v13
	v_mul_f32_e64 v12, v144, v92
	v_mul_f32_e64 v13, v144, v93
	v_mul_f32_e64 v56, v14, v12
	v_mul_f32_e64 v57, v15, v13
	ds_read_b128 v[12:15], v164 offset:61696
	v_cvt_pk_bf16_f32 v121, v56, v57
	s_mov_b32 s17, s8
	s_waitcnt lgkmcnt(1)
	v_mfma_f32_32x32x16_bf16 v[32:47], v[48:51], v[112:115], v[32:47]
	v_mul_f32_e64 v48, v144, v90
	v_mul_f32_e64 v49, v144, v91
	v_mul_f32_e64 v8, v8, v48
	v_mul_f32_e64 v9, v9, v49
	v_mul_f32_e64 v48, v144, v86
	v_mul_f32_e64 v49, v144, v87
	v_cvt_pk_bf16_f32 v122, v8, v9
	v_pk_mul_f32 v[8:9], v[144:145], v[88:89] op_sel_hi:[0,1]
	v_pk_mul_f32 v[8:9], v[10:11], v[8:9]
	v_pk_mul_f32 v[4:5], v[4:5], v[48:49]
	v_cvt_pk_bf16_f32 v123, v8, v9
	ds_read_b128 v[8:11], v165 offset:61568
	v_mfma_f32_32x32x16_bf16 v[16:31], v[168:171], v[112:115], v[16:31]
	v_cvt_pk_bf16_f32 v124, v4, v5
	v_mul_f32_e64 v4, v144, v84
	v_mul_f32_e64 v5, v144, v85
	v_mul_f32_e64 v48, v6, v4
	v_mul_f32_e64 v49, v7, v5
	ds_read_b128 v[4:7], v165 offset:61696
	v_cvt_pk_bf16_f32 v125, v48, v49
	v_lshl_add_u64 v[164:165], s[46:47], 0, v[136:137]
	s_mov_b32 s18, s8
	v_mfma_f32_32x32x16_bf16 v[16:31], v[150:153], v[120:123], v[16:31]
	s_mov_b32 s19, s8
	s_mov_b32 s20, s8
	s_mov_b32 s21, s8
	s_mov_b32 s22, s8
	s_mov_b32 s23, s8
	s_mov_b32 s48, 2
	s_mov_b32 s49, 1
	s_waitcnt lgkmcnt(1)
	v_mfma_f32_32x32x16_bf16 v[32:47], v[8:11], v[120:123], v[32:47]
	v_mul_f32_e64 v8, v144, v82
	v_mul_f32_e64 v9, v144, v83
	v_mul_f32_e64 v0, v8, v0
	v_mul_f32_e64 v1, v9, v1
	v_cmp_gt_u32_e64 s[4:5], 32, v187
	v_cvt_pk_bf16_f32 v126, v0, v1
	v_pk_mul_f32 v[0:1], v[144:145], v[80:81] op_sel_hi:[0,1]
	v_pk_mul_f32 v[0:1], v[0:1], v[2:3]
	v_mov_b32_e32 v170, 0
	v_cvt_pk_bf16_f32 v127, v0, v1
	ds_read_b128 v[0:3], v130 offset:61568
	ds_read_b128 v[48:51], v130 offset:61696
	v_mfma_f32_32x32x16_bf16 v[16:31], v[64:67], v[124:127], v[16:31]
	s_waitcnt lgkmcnt(1)
	v_mfma_f32_32x32x16_bf16 v[32:47], v[0:3], v[124:127], v[32:47]
	ds_read_b128 v[0:3], v161
	ds_read_b128 v[8:11], v161 offset:1024
	s_waitcnt lgkmcnt(1)
	v_mfma_f32_32x32x16_bf16 v[16:31], v[154:157], v[0:3], v[16:31]
	v_mfma_f32_32x32x16_bf16 v[32:47], v[52:55], v[0:3], v[32:47]
	v_lshl_add_u64 v[0:1], v[162:163], 0, s[2:3]
	v_lshlrev_b64 v[0:1], 11, v[0:1]
	v_lshl_add_u64 v[0:1], s[46:47], 0, v[0:1]
	s_lshl_b64 s[2:3], s[2:3], 7
	v_lshl_add_u64 v[0:1], v[0:1], 0, v[136:137]
	s_add_u32 s2, s26, s2
	v_add_co_u32_e32 v2, vcc, s73, v0
	s_addc_u32 s3, s27, s3
	s_nop 0
	v_addc_co_u32_e32 v3, vcc, 0, v1, vcc
	global_load_dwordx4 v[52:55], v[0:1], off
	global_load_dwordx4 v[56:59], v[0:1], off offset:256
	global_load_dwordx4 v[64:67], v[2:3], off
	global_load_dwordx4 v[68:71], v[2:3], off offset:256
	v_lshl_add_u64 v[0:1], s[2:3], 0, v[140:141]
	global_load_dwordx4 v[76:79], v[0:1], off
	s_waitcnt lgkmcnt(0)
	v_mfma_f32_32x32x16_bf16 v[16:31], v[132:135], v[8:11], v[16:31]
	v_and_b32_e32 v0, 0x3fffffc0, v178
	v_lshl_add_u32 v168, v0, 2, s0
	ds_read_b128 v[0:3], v161 offset:2048
	ds_read_b128 v[80:83], v161 offset:3072
	s_add_i32 s0, 0, 0x12000
	s_waitcnt vmcnt(0)
	s_waitcnt vmcnt(3)
	ds_write_b128 v145, v[56:59] offset:16384
	s_waitcnt vmcnt(1)
	ds_write_b128 v158, v[68:71] offset:16384
	v_mfma_f32_32x32x16_bf16 v[32:47], v[12:15], v[8:11], v[32:47]
	v_lshlrev_b32_e32 v8, 3, v187
	v_and_b32_e32 v9, 0xc0, v166
	v_lshlrev_b32_e32 v10, 1, v187
	v_and_or_b32 v9, v8, 24, v9
	v_and_b32_e32 v10, 32, v10
	v_and_b32_e32 v8, 0x100, v8
	v_or3_b32 v8, v9, v10, v8
	s_waitcnt lgkmcnt(3)
	v_mfma_f32_32x32x16_bf16 v[16:31], v[72:75], v[0:3], v[16:31]
	v_lshl_add_u64 v[166:167], s[26:27], 0, v[140:141]
	v_add_u32_e32 v171, s1, v8
	v_lshl_add_u32 v169, v176, 2, v168
	v_mfma_f32_32x32x16_bf16 v[32:47], v[4:7], v[0:3], v[32:47]
	v_mov_b64_e32 v[0:1], s[8:9]
	v_mov_b64_e32 v[14:15], s[22:23]
	v_mov_b64_e32 v[2:3], s[10:11]
	v_mov_b64_e32 v[4:5], s[12:13]
	v_mov_b64_e32 v[6:7], s[14:15]
	v_mov_b64_e32 v[8:9], s[16:17]
	v_mov_b64_e32 v[10:11], s[18:19]
	s_waitcnt lgkmcnt(2)
; #define SBAR() __builtin_amdgcn_sched_barrier(0)
; #define SLOAD(k0) do { const long rb = KROW(k0); const bf16* pn = KN + (rb + sr) * LDKN + sc; \
;     ks0 = *reinterpret_cast<const bf16x8*>(pn); ks1 = *reinterpret_cast<const bf16x8*>(pn + 32 * LDKN); vs0 = *reinterpret_cast<const bf16x8*>(pn + 128); vs1 = *reinterpret_cast<const bf16x8*>(pn + 32 * LDKN + 128); \
;     ks2 = *reinterpret_cast<const bf16x8*>(KR + rb * LDKR + tid * 8); } while (0)
; #define SWRITE(b) do { *(bf16x8*)(V_lds + (b) * SHM_V + vst0) = vs0; *(bf16x8*)(V_lds + (b) * SHM_V + vst1) = vs1; \
;     *(bf16x8*)(K_lds + (b) * SHM_K + knd0) = ks0; *(bf16x8*)(K_lds + (b) * SHM_K + knd1) = ks1; *(bf16x8*)(K_lds + (b) * SHM_K + krd) = ks2; } while (0)
; #define SWAIT() asm volatile("s_waitcnt vmcnt(0)" ::: "memory")
; __device__ __forceinline__ void partialSM(f32x16& p0, f32x16& p1, float& m_reg, float& mn, float& alpha) {
;   constexpr float C = SCALE * 1.4426950408889634f;
;   float pmax = p0[0]; for (int r = 1; r < 16; ++r) pmax = fmaxf(pmax, p0[r]); for (int r = 0; r < 16; ++r) pmax = fmaxf(pmax, p1[r]);
;   { auto rr = __builtin_amdgcn_permlane32_swap(__float_as_uint(pmax), __float_as_uint(pmax), false, false);
;     pmax = fmaxf(__uint_as_float(rr[0]), __uint_as_float(rr[1])); }
;   if (__builtin_expect(__all(pmax - m_reg <= THR / SCALE), 1)) { mn = m_reg; alpha = 1.f; }
;   else { mn = fmaxf(m_reg, pmax); alpha = __builtin_amdgcn_exp2f((m_reg - mn) * C); m_reg = mn; }
;   float mnC = -mn * C;
;   for (int r = 0; r < 16; ++r) p0[r] = fmaf(p0[r], C, mnC); for (int r = 0; r < 16; ++r) p1[r] = fmaf(p1[r], C, mnC);
;   for (int r = 0; r < 16; ++r) p0[r] = __builtin_amdgcn_exp2f(p0[r]);
; }
; __device__ __forceinline__ void attn_unit(const bf16* __restrict__ Qb, const bf16* __restrict__ KN, const bf16* __restrict__ KR, ...
;     ...
;   SLOAD(0); SWAIT(); SWRITE(0); __syncthreads();
;   qkt(pA0, pA1, K_lds, qr, qs, kb); partialSM(pA0, pA1, m_reg, mnA, alA);
;   SLOAD(KVBLK); SWAIT(); SWRITE(1); __syncthreads();
;   int rp = 0, rc = 1, rn = 2;
;   for (int j = 1; j + 1 < NT; j += 2) {
;     SBAR(); qkt(pB0, pB1, K_lds + rc * SHM_K, qr, qs, kb);
	v_mfma_f32_32x32x16_bf16 v[16:31], v[60:63], v[80:83], v[16:31]
	v_mov_b64_e32 v[12:13], s[20:21]
	s_mov_b64 s[10:11], 0x80
	v_mfma_f32_32x32x16_bf16 v[32:47], v[48:51], v[80:83], v[32:47]
	s_nop 8
	v_max_f32_e32 v48, v17, v17
	v_max_f32_e32 v49, v16, v16
	v_max_f32_e32 v48, v49, v48
	v_max3_f32 v48, v48, v18, v19
	v_max3_f32 v48, v48, v20, v21
	v_max3_f32 v48, v48, v22, v23
	v_max3_f32 v48, v48, v24, v25
	v_max3_f32 v48, v48, v26, v27
	v_max3_f32 v48, v48, v28, v29
	v_max3_f32 v48, v48, v30, v31
	v_max3_f32 v48, v48, v32, v33
	v_max3_f32 v48, v48, v34, v35
	v_max3_f32 v48, v48, v36, v37
	v_max3_f32 v48, v48, v38, v39
	v_max3_f32 v48, v48, v40, v41
	v_max3_f32 v48, v48, v42, v43
	v_max3_f32 v48, v48, v44, v45
	v_max3_f32 v48, v48, v46, v47
	v_mov_b32_e32 v49, v48
	s_nop 1
	v_permlane32_swap_b32_e32 v48, v49
	v_max_f32_e32 v49, v49, v49
	v_max_f32_e32 v48, v48, v48
	v_max_f32_e32 v48, v48, v49
	v_add_f32_e32 v49, 0x7149f2ca, v48
	v_cmp_ge_f32_e32 vcc, s74, v49
	v_add_u32_e32 v49, s0, v179
	ds_write_b128 v49, v[52:55]
	ds_write_b128 v49, v[64:67] offset:12288
	v_add_u32_e32 v49, s0, v180
	s_cmp_eq_u64 vcc, exec
	s_waitcnt vmcnt(0)
	ds_write_b128 v49, v[76:79]
	v_max_f32_e32 v49, 0xf149f2ca, v48
	s_cselect_b64 vcc, -1, 0
	v_mov_b32_e32 v48, 0xf149f2ca
	v_cndmask_b32_e32 v178, v49, v48, vcc
	v_mul_f32_e32 v48, 0xbdd53b94, v178
	v_fmamk_f32 v16, v16, 0x3dd53b94, v48
	v_exp_f32_e32 v149, v16
	v_fmamk_f32 v16, v17, 0x3dd53b94, v48
	v_exp_f32_e32 v150, v16
	v_fmamk_f32 v16, v18, 0x3dd53b94, v48
	v_exp_f32_e32 v151, v16
	v_fmamk_f32 v16, v19, 0x3dd53b94, v48
	v_exp_f32_e32 v157, v16
	v_fmamk_f32 v16, v20, 0x3dd53b94, v48
	v_exp_f32_e32 v159, v16
	v_fmamk_f32 v16, v21, 0x3dd53b94, v48
	v_exp_f32_e32 v188, v16
	v_fmamk_f32 v16, v22, 0x3dd53b94, v48
	v_exp_f32_e32 v152, v16
	v_fmamk_f32 v16, v23, 0x3dd53b94, v48
	v_exp_f32_e32 v158, v16
	v_fmamk_f32 v16, v24, 0x3dd53b94, v48
	v_exp_f32_e32 v144, v16
	v_fmamk_f32 v16, v25, 0x3dd53b94, v48
	v_exp_f32_e32 v146, v16
	v_fmamk_f32 v16, v26, 0x3dd53b94, v48
	v_pk_fma_f32 v[136:137], v[38:39], s[68:69], v[48:49] op_sel_hi:[1,0,0]
	v_sub_f32_e32 v38, 0xf149f2ca, v49
	v_exp_f32_e32 v153, v16
	v_fmamk_f32 v16, v27, 0x3dd53b94, v48
	v_mul_f32_e32 v38, 0x3dd53b94, v38
	v_exp_f32_e32 v154, v16
	v_fmamk_f32 v16, v28, 0x3dd53b94, v48
	v_exp_f32_e32 v38, v38
	v_exp_f32_e32 v145, v16
	v_fmamk_f32 v16, v29, 0x3dd53b94, v48
	v_pk_fma_f32 v[128:129], v[46:47], s[68:69], v[48:49] op_sel_hi:[1,0,0]
	v_pk_fma_f32 v[130:131], v[44:45], s[68:69], v[48:49] op_sel_hi:[1,0,0]
	v_pk_fma_f32 v[132:133], v[42:43], s[68:69], v[48:49] op_sel_hi:[1,0,0]
	v_pk_fma_f32 v[134:135], v[40:41], s[68:69], v[48:49] op_sel_hi:[1,0,0]
	v_pk_fma_f32 v[138:139], v[36:37], s[68:69], v[48:49] op_sel_hi:[1,0,0]
	v_pk_fma_f32 v[140:141], v[34:35], s[68:69], v[48:49] op_sel_hi:[1,0,0]
	v_pk_fma_f32 v[142:143], v[32:33], s[68:69], v[48:49] op_sel_hi:[1,0,0]
	v_exp_f32_e32 v147, v16
	v_fmamk_f32 v16, v30, 0x3dd53b94, v48
	v_fmac_f32_e32 v48, 0x3dd53b94, v31
	v_exp_f32_e32 v155, v16
	v_exp_f32_e32 v156, v48
	v_cndmask_b32_e64 v184, v38, 1.0, vcc
	v_mov_b64_e32 v[62:63], v[14:15]
	v_mov_b64_e32 v[46:47], v[14:15]
	v_mov_b64_e32 v[30:31], v[14:15]
	v_mov_b64_e32 v[60:61], v[12:13]
	v_mov_b64_e32 v[58:59], v[10:11]
	v_mov_b64_e32 v[56:57], v[8:9]
	v_mov_b64_e32 v[54:55], v[6:7]
	v_mov_b64_e32 v[52:53], v[4:5]
	v_mov_b64_e32 v[50:51], v[2:3]
	v_mov_b64_e32 v[48:49], v[0:1]
	v_mov_b64_e32 v[44:45], v[12:13]
	v_mov_b64_e32 v[42:43], v[10:11]
	v_mov_b64_e32 v[40:41], v[8:9]
	v_mov_b64_e32 v[38:39], v[6:7]
	v_mov_b64_e32 v[36:37], v[4:5]
	v_mov_b64_e32 v[34:35], v[2:3]
	v_mov_b64_e32 v[32:33], v[0:1]
	v_mov_b64_e32 v[28:29], v[12:13]
	v_mov_b64_e32 v[26:27], v[10:11]
	v_mov_b64_e32 v[24:25], v[8:9]
	v_mov_b64_e32 v[22:23], v[6:7]
	v_mov_b64_e32 v[20:21], v[4:5]
	v_mov_b64_e32 v[18:19], v[2:3]
	v_mov_b64_e32 v[16:17], v[0:1]
	s_mov_b32 s0, 2
	s_waitcnt lgkmcnt(0)
	s_barrier
	s_mov_b32 s9, s0
	v_mov_b32_e32 v249, v184
	ds_read_b128 v[226:229], v161 offset:0
	ds_read_b128 v[230:233], v161 offset:1024
	ds_read_b128 v[234:237], v161 offset:2048
	ds_read_b128 v[238:241], v161 offset:3072
	v_mov_b32_e32 v80, v149
	v_mov_b32_e32 v81, v150
	v_mov_b32_e32 v82, v151
	v_mov_b32_e32 v83, v157
	v_mov_b32_e32 v84, v159
	v_mov_b32_e32 v85, v188
	v_mov_b32_e32 v86, v152
	v_mov_b32_e32 v87, v158
	v_mov_b32_e32 v88, v144
	v_mov_b32_e32 v89, v146
	v_mov_b32_e32 v90, v153
	v_mov_b32_e32 v91, v154
	v_mov_b32_e32 v92, v145
	v_mov_b32_e32 v93, v147
	v_mov_b32_e32 v94, v155
	v_mov_b32_e32 v95, v156
	v_mov_b32_e32 v64, v142
	v_mov_b32_e32 v65, v143
	v_mov_b32_e32 v66, v140
	v_mov_b32_e32 v67, v141
	v_mov_b32_e32 v68, v138
	v_mov_b32_e32 v69, v139
	v_mov_b32_e32 v70, v136
	v_mov_b32_e32 v71, v137
	v_mov_b32_e32 v72, v134
	v_mov_b32_e32 v73, v135
	v_mov_b32_e32 v74, v132
	v_mov_b32_e32 v75, v133
	v_mov_b32_e32 v76, v130
	v_mov_b32_e32 v77, v131
	v_mov_b32_e32 v78, v128
	v_mov_b32_e32 v79, v129
	v_readfirstlane_b32 s1, v242
	s_nop 3
	s_lshr_b32 s1, s1, 6
	s_cmp_ge_u32 s1, 4
	s_cbranch_scc0 .Lattn_noprio
	s_setprio 1
.Lattn_noprio:
	s_waitcnt lgkmcnt(0)
; #define SBAR() __builtin_amdgcn_sched_barrier(0)
; #define SLOAD(k0) do { const long rb = KROW(k0); const bf16* pn = KN + (rb + sr) * LDKN + sc; \
;     ks0 = *reinterpret_cast<const bf16x8*>(pn); ks1 = *reinterpret_cast<const bf16x8*>(pn + 32 * LDKN); vs0 = *reinterpret_cast<const bf16x8*>(pn + 128); vs1 = *reinterpret_cast<const bf16x8*>(pn + 32 * LDKN + 128); \
;     ks2 = *reinterpret_cast<const bf16x8*>(KR + rb * LDKR + tid * 8); } while (0)
; __device__ __forceinline__ void finishSM(f32x16& p0, f32x16& p1, float alpha, float& l_reg, bf16x8& pa0, bf16x8& pa1, bf16x8& pa2, bf16x8& pa3) {
;   for (int r = 0; r < 16; ++r) p1[r] = __builtin_amdgcn_exp2f(p1[r]);
;   float ps = 0; for (int r = 0; r < 16; ++r) ps += p0[r]; for (int r = 0; r < 16; ++r) ps += p1[r];
;   { auto rr = __builtin_amdgcn_permlane32_swap(__float_as_uint(ps), __float_as_uint(ps), false, false);
;     ps = __uint_as_float(rr[0]) + __uint_as_float(rr[1]); }
;   l_reg = l_reg * alpha + ps;
;     ...
;   PK4(p0, 0, pa0); PK4(p0, 8, pa1); PK4(p1, 0, pa2); PK4(p1, 8, pa3);
;     ...
; }
; __device__ __forceinline__ void attn_unit(const bf16* __restrict__ Qb, const bf16* __restrict__ KN, const bf16* __restrict__ KR, ...
;     ...
;   for (int j = 1; j + 1 < NT; j += 2) {
;     SBAR(); qkt(pB0, pB1, K_lds + rc * SHM_K, qr, qs, kb);
;     finishSM(pA0, pA1, alA, l_reg, pa0, pa1, pa2, pa3); SBAR();
;     SLOAD((j + 1) * KVBLK); SBAR();
.LBB0_107:
	s_mul_i32 s0, s49, 0x6000
	v_add_u32_e32 v250, s0, v173
	v_add_u32_e32 v251, s0, v181
	v_add_u32_e32 v252, s0, v182
	v_add_u32_e32 v172, s0, v183
	v_lshl_add_u32 v246, s8, 14, v171
	ds_read_b128 v[210:213], v250 offset:49152
	ds_read_b128 v[214:217], v250 offset:61440
	ds_read_b128 v[218:221], v251 offset:49152
	ds_read_b128 v[222:225], v251 offset:61440
	v_cvt_pk_bf16_f32 v188, v80, v81
	v_cvt_pk_bf16_f32 v189, v82, v83
	v_cvt_pk_bf16_f32 v190, v84, v85
	v_cvt_pk_bf16_f32 v191, v86, v87
	v_cvt_pk_bf16_f32 v192, v88, v89
	v_cvt_pk_bf16_f32 v193, v90, v91
	v_cvt_pk_bf16_f32 v194, v92, v93
	v_cvt_pk_bf16_f32 v195, v94, v95
	s_waitcnt lgkmcnt(2)
	v_mfma_f32_32x32x16_bf16 v[144:159], v[210:213], v[96:99], 0
	v_permlane32_swap_b32_e32 v188, v190
	v_permlane32_swap_b32_e32 v189, v191
	v_exp_f32_e32 v64, v64
	v_mfma_f32_32x32x16_bf16 v[128:143], v[214:217], v[96:99], 0
	ds_read_b128 v[210:213], v252 offset:49152
	ds_read_b128 v[214:217], v252 offset:61440
	v_permlane32_swap_b32_e32 v192, v194
	v_permlane32_swap_b32_e32 v193, v195
	v_exp_f32_e32 v65, v65
	s_waitcnt lgkmcnt(2)
	v_mfma_f32_32x32x16_bf16 v[144:159], v[218:221], v[100:103], v[144:159]
	v_add_f32_e32 v255, v80, v81
	v_add_f32_e32 v255, v82, v255
	v_exp_f32_e32 v66, v66
	v_mfma_f32_32x32x16_bf16 v[128:143], v[222:225], v[100:103], v[128:143]
	ds_read_b128 v[218:221], v172 offset:49152
	ds_read_b128 v[222:225], v172 offset:61440
	v_add_f32_e32 v255, v83, v255
	v_add_f32_e32 v255, v84, v255
	v_exp_f32_e32 v67, v67
	s_waitcnt lgkmcnt(2)
	v_mfma_f32_32x32x16_bf16 v[144:159], v[210:213], v[104:107], v[144:159]
	v_add_f32_e32 v255, v85, v255
	v_add_f32_e32 v255, v86, v255
	v_exp_f32_e32 v68, v68
	v_mfma_f32_32x32x16_bf16 v[128:143], v[214:217], v[104:107], v[128:143]
	ds_read_b128 v[210:213], v250 offset:49280
	ds_read_b128 v[214:217], v250 offset:61568
	v_add_f32_e32 v255, v87, v255
	v_add_f32_e32 v255, v88, v255
	v_exp_f32_e32 v69, v69
	s_waitcnt lgkmcnt(2)
	v_mfma_f32_32x32x16_bf16 v[144:159], v[218:221], v[116:119], v[144:159]
	v_add_f32_e32 v255, v89, v255
	v_add_f32_e32 v255, v90, v255
	v_exp_f32_e32 v70, v70
	v_mfma_f32_32x32x16_bf16 v[128:143], v[222:225], v[116:119], v[128:143]
	ds_read_b128 v[218:221], v251 offset:49280
	ds_read_b128 v[222:225], v251 offset:61568
	v_add_f32_e32 v255, v91, v255
	v_add_f32_e32 v255, v92, v255
	v_exp_f32_e32 v71, v71
	s_waitcnt lgkmcnt(2)
	v_mfma_f32_32x32x16_bf16 v[144:159], v[210:213], v[108:111], v[144:159]
	v_add_f32_e32 v255, v93, v255
	v_add_f32_e32 v255, v94, v255
	v_mfma_f32_32x32x16_bf16 v[128:143], v[214:217], v[108:111], v[128:143]
	ds_read_b128 v[210:213], v252 offset:49280
	ds_read_b128 v[214:217], v252 offset:61568
	v_exp_f32_e32 v72, v72
	v_add_f32_e32 v255, v95, v255
	v_cvt_pk_bf16_f32 v196, v64, v65
	s_cmp_lt_u32 s10, s42
	s_cselect_b32 s0, s44, s45
	s_ashr_i32 s1, s0, 31
	s_add_u32 s0, s10, s0
	s_addc_u32 s1, s11, s1
	v_lshl_add_u64 v[80:81], s[0:1], 0, v[162:163]
	v_lshlrev_b64 v[80:81], 11, v[80:81]
	v_lshl_add_u64 v[88:89], v[164:165], 0, v[80:81]
	v_add_co_u32_e32 v92, vcc, s73, v88
	s_lshl_b64 s[0:1], s[0:1], 7
	s_nop 0
	v_addc_co_u32_e32 v93, vcc, 0, v89, vcc
	v_lshl_add_u64 v[204:205], v[166:167], 0, s[0:1]
	s_waitcnt lgkmcnt(2)
	v_mfma_f32_32x32x16_bf16 v[144:159], v[218:221], v[112:115], v[144:159]
	v_cvt_pk_bf16_f32 v197, v66, v67
	v_cvt_pk_bf16_f32 v198, v68, v69
	v_cvt_pk_bf16_f32 v199, v70, v71
	v_add_f32_e32 v203, v64, v65
	global_load_dwordx4 v[80:83], v[88:89], off
	global_load_dwordx4 v[84:87], v[88:89], off offset:256
	s_nop 0
	global_load_dwordx4 v[88:91], v[92:93], off
	global_load_dwordx4 v[92:95], v[92:93], off offset:256
	global_load_dwordx4 v[204:207], v[204:205], off
	v_mfma_f32_32x32x16_bf16 v[128:143], v[222:225], v[112:115], v[128:143]
	ds_read_b128 v[218:221], v172 offset:49280
	ds_read_b128 v[222:225], v172 offset:61568
	v_add_f32_e32 v203, v66, v203
	v_exp_f32_e32 v73, v73
	v_add_f32_e32 v203, v67, v203
	s_waitcnt lgkmcnt(2)
	v_mfma_f32_32x32x16_bf16 v[144:159], v[210:213], v[120:123], v[144:159]
	v_add_f32_e32 v203, v68, v203
	v_exp_f32_e32 v74, v74
	v_add_f32_e32 v203, v69, v203
	v_mfma_f32_32x32x16_bf16 v[128:143], v[214:217], v[120:123], v[128:143]
	ds_read_b128 v[210:213], v250 offset:49408
	ds_read_b128 v[214:217], v250 offset:61696
	v_add_f32_e32 v203, v70, v203
	v_exp_f32_e32 v75, v75
	s_waitcnt lgkmcnt(2)
	v_mfma_f32_32x32x16_bf16 v[144:159], v[218:221], v[124:127], v[144:159]
	v_add_f32_e32 v203, v71, v203
	v_add_f32_e32 v203, v72, v203
	v_exp_f32_e32 v76, v76
	v_mfma_f32_32x32x16_bf16 v[128:143], v[222:225], v[124:127], v[128:143]
	ds_read_b128 v[218:221], v251 offset:49408
	ds_read_b128 v[222:225], v251 offset:61696
	v_permlane32_swap_b32_e32 v196, v198
	v_permlane32_swap_b32_e32 v197, v199
	v_exp_f32_e32 v77, v77
	s_waitcnt lgkmcnt(2)
	v_mfma_f32_32x32x16_bf16 v[144:159], v[210:213], v[226:229], v[144:159]
	v_add_f32_e32 v203, v73, v203
	v_add_f32_e32 v203, v74, v203
	v_exp_f32_e32 v78, v78
	v_mfma_f32_32x32x16_bf16 v[128:143], v[214:217], v[226:229], v[128:143]
	ds_read_b128 v[210:213], v252 offset:49408
	ds_read_b128 v[214:217], v252 offset:61696
	v_add_f32_e32 v203, v75, v203
	v_add_f32_e32 v203, v76, v203
	v_exp_f32_e32 v79, v79
	s_waitcnt lgkmcnt(2)
	v_mfma_f32_32x32x16_bf16 v[144:159], v[218:221], v[230:233], v[144:159]
	v_add_f32_e32 v203, v77, v203
	v_add_f32_e32 v203, v78, v203
	v_add_f32_e32 v203, v79, v203
	v_mfma_f32_32x32x16_bf16 v[128:143], v[222:225], v[230:233], v[128:143]
	ds_read_b128 v[218:221], v172 offset:49408
	ds_read_b128 v[222:225], v172 offset:61696
	v_add_f32_e32 v255, v255, v203
	v_mov_b32_e32 v202, v255
	s_nop 1
	v_permlane32_swap_b32_e32 v255, v202
	v_add_f32_e32 v255, v255, v202
	s_waitcnt lgkmcnt(2)
; #define PV_WAIT(n, f) asm volatile("s_waitcnt lgkmcnt(" #n ")" : "+v"(f[0]), "+v"(f[1]), "+v"(f[2]), "+v"(f[3]), "+v"(f[4]), "+v"(f[5]), "+v"(f[6]), "+v"(f[7]))
; __device__ __forceinline__ void partialSM(f32x16& p0, f32x16& p1, float& m_reg, float& mn, float& alpha) {
;   constexpr float C = SCALE * 1.4426950408889634f;
;   float pmax = p0[0]; for (int r = 1; r < 16; ++r) pmax = fmaxf(pmax, p0[r]); for (int r = 0; r < 16; ++r) pmax = fmaxf(pmax, p1[r]);
;   { auto rr = __builtin_amdgcn_permlane32_swap(__float_as_uint(pmax), __float_as_uint(pmax), false, false);
;     pmax = fmaxf(__uint_as_float(rr[0]), __uint_as_float(rr[1])); }
;   if (__builtin_expect(__all(pmax - m_reg <= THR / SCALE), 1)) { mn = m_reg; alpha = 1.f; }
;   else { mn = fmaxf(m_reg, pmax); alpha = __builtin_amdgcn_exp2f((m_reg - mn) * C); m_reg = mn; }
;   float mnC = -mn * C;
;   for (int r = 0; r < 16; ++r) p0[r] = fmaf(p0[r], C, mnC); for (int r = 0; r < 16; ++r) p1[r] = fmaf(p1[r], C, mnC);
;   for (int r = 0; r < 16; ++r) p0[r] = __builtin_amdgcn_exp2f(p0[r]);
; }
; __device__ __forceinline__ void pv_d0(f32x16* o, int vb, bf16x8 pa0, bf16x8 pa1, bf16x8 pa2, bf16x8 pa3) {
;   s16x4 fa[8], fb[8];
;   pv_rd<0>(fa, vb); pv_rd<1>(fb, vb);
;   PV_WAIT(8, fa); pv_mm(o[0], fa, pa0, pa1, pa2, pa3);
;   pv_rd<2>(fa, vb);
;   PV_WAIT(8, fb); pv_mm(o[1], fb, pa0, pa1, pa2, pa3);
;   pv_rd<3>(fb, vb);
;   PV_WAIT(8, fa); pv_mm(o[2], fa, pa0, pa1, pa2, pa3);
;   PV_WAIT(0, fb); pv_mm(o[3], fb, pa0, pa1, pa2, pa3);
; }
	v_mfma_f32_32x32x16_bf16 v[144:159], v[210:213], v[234:237], v[144:159]
	v_fma_f32 v170, v170, v249, v255
	v_cvt_pk_bf16_f32 v200, v72, v73
	v_cvt_pk_bf16_f32 v201, v74, v75
	v_cvt_pk_bf16_f32 v202, v76, v77
	v_mfma_f32_32x32x16_bf16 v[128:143], v[214:217], v[234:237], v[128:143]
	ds_read_b64_tr_b16 v[210:211], v246 offset:0
	ds_read_b64_tr_b16 v[212:213], v246 offset:2048
	ds_read_b64_tr_b16 v[214:215], v246 offset:4096
	ds_read_b64_tr_b16 v[216:217], v246 offset:6144
	v_cvt_pk_bf16_f32 v203, v78, v79
	v_permlane32_swap_b32_e32 v200, v202
	s_nop 0
	v_permlane32_swap_b32_e32 v201, v203
	s_waitcnt lgkmcnt(4)
	v_mfma_f32_32x32x16_bf16 v[144:159], v[218:221], v[238:241], v[144:159]
	v_mfma_f32_32x32x16_bf16 v[128:143], v[222:225], v[238:241], v[128:143]
	ds_read_b64_tr_b16 v[218:219], v246 offset:8192
	ds_read_b64_tr_b16 v[220:221], v246 offset:10240
	ds_read_b64_tr_b16 v[222:223], v246 offset:12288
	ds_read_b64_tr_b16 v[224:225], v246 offset:14336
	ds_read_b64_tr_b16 v[184:185], v246 offset:512
	ds_read_b64_tr_b16 v[186:187], v246 offset:2560
	s_lshl_b32 s14, s9, 14
	s_lshl_b32 s1, s9, 13
	s_add_i32 s15, s14, s1
	s_waitcnt lgkmcnt(6)
	v_mfma_f32_32x32x16_bf16 v[0:15], v[188:191], v[210:213], v[0:15]
	ds_read_b64_tr_b16 v[210:211], v246 offset:4608
	ds_read_b64_tr_b16 v[212:213], v246 offset:6656
	v_max3_f32 v64, v144, v145, v146
	v_max3_f32 v65, v128, v129, v130
	v_max3_f32 v64, v64, v147, v148
	v_max3_f32 v65, v65, v131, v132
	v_max3_f32 v64, v64, v149, v150
	v_max3_f32 v65, v65, v133, v134
	v_mfma_f32_32x32x16_bf16 v[0:15], v[192:195], v[214:217], v[0:15]
	ds_read_b64_tr_b16 v[214:215], v246 offset:8704
	ds_read_b64_tr_b16 v[216:217], v246 offset:10752
	v_max3_f32 v64, v64, v151, v152
	v_max3_f32 v65, v65, v135, v136
	v_max3_f32 v64, v64, v153, v154
	v_max3_f32 v65, v65, v137, v138
	v_max3_f32 v64, v64, v155, v156
	v_max3_f32 v65, v65, v139, v140
	s_waitcnt lgkmcnt(6)
	v_mfma_f32_32x32x16_bf16 v[0:15], v[196:199], v[218:221], v[0:15]
	ds_read_b64_tr_b16 v[218:219], v246 offset:12800
	ds_read_b64_tr_b16 v[220:221], v246 offset:14848
	v_max3_f32 v64, v64, v157, v158
	v_max3_f32 v65, v65, v141, v142
	v_max_f32_e32 v64, v64, v159
	v_max_f32_e32 v65, v65, v143
	v_max_f32_e32 v64, v64, v65
	v_mov_b32_e32 v66, v64
	v_mfma_f32_32x32x16_bf16 v[0:15], v[200:203], v[222:225], v[0:15]
	ds_read_b64_tr_b16 v[222:223], v246 offset:1024
	ds_read_b64_tr_b16 v[224:225], v246 offset:3072
	v_permlane32_swap_b32_e32 v64, v66
	v_max_f32_e32 v64, v64, v66
	v_sub_f32_e32 v67, v64, v178
	v_cmp_ge_f32_e32 vcc, s74, v67
	v_max_f32_e32 v68, v178, v64
	v_sub_f32_e32 v67, v178, v68
	s_waitcnt lgkmcnt(6)
	v_mfma_f32_32x32x16_bf16 v[48:63], v[188:191], v[184:187], v[48:63]
	ds_read_b64_tr_b16 v[184:185], v246 offset:5120
	ds_read_b64_tr_b16 v[186:187], v246 offset:7168
	v_mul_f32_e32 v67, 0x3dd53b94, v67
	v_exp_f32_e32 v67, v67
	s_cmp_eq_u64 vcc, exec
	s_cselect_b64 s[6:7], -1, 0
	v_cndmask_b32_e64 v249, v67, 1.0, s[6:7]
	v_cndmask_b32_e64 v178, v68, v178, s[6:7]
	v_mfma_f32_32x32x16_bf16 v[48:63], v[192:195], v[210:213], v[48:63]
	ds_read_b64_tr_b16 v[210:211], v246 offset:9216
	ds_read_b64_tr_b16 v[212:213], v246 offset:11264
	v_mul_f32_e32 v69, 0xbdd53b94, v178
	v_cmp_gt_f32_e32 vcc, 1.0, v249
	v_fmamk_f32 v144, v144, 0x3dd53b94, v69
	v_fmamk_f32 v145, v145, 0x3dd53b94, v69
	v_fmamk_f32 v146, v146, 0x3dd53b94, v69
	v_fmamk_f32 v147, v147, 0x3dd53b94, v69
	s_waitcnt lgkmcnt(6)
	v_mfma_f32_32x32x16_bf16 v[48:63], v[196:199], v[214:217], v[48:63]
	ds_read_b64_tr_b16 v[214:215], v246 offset:13312
	ds_read_b64_tr_b16 v[216:217], v246 offset:15360
	v_fmamk_f32 v148, v148, 0x3dd53b94, v69
	v_fmamk_f32 v149, v149, 0x3dd53b94, v69
	v_fmamk_f32 v150, v150, 0x3dd53b94, v69
	v_fmamk_f32 v151, v151, 0x3dd53b94, v69
	v_fmamk_f32 v152, v152, 0x3dd53b94, v69
	v_exp_f32_e32 v144, v144
	v_mfma_f32_32x32x16_bf16 v[48:63], v[200:203], v[218:221], v[48:63]
	ds_read_b64_tr_b16 v[218:219], v246 offset:1536
	ds_read_b64_tr_b16 v[220:221], v246 offset:3584
	v_fmamk_f32 v153, v153, 0x3dd53b94, v69
	v_exp_f32_e32 v145, v145
	v_fmamk_f32 v154, v154, 0x3dd53b94, v69
	v_exp_f32_e32 v146, v146
	s_waitcnt lgkmcnt(6)
	v_mfma_f32_32x32x16_bf16 v[32:47], v[188:191], v[222:225], v[32:47]
	ds_read_b64_tr_b16 v[222:223], v246 offset:5632
	ds_read_b64_tr_b16 v[224:225], v246 offset:7680
	v_fmamk_f32 v155, v155, 0x3dd53b94, v69
	v_exp_f32_e32 v147, v147
	v_fmamk_f32 v156, v156, 0x3dd53b94, v69
	v_exp_f32_e32 v148, v148
	v_mfma_f32_32x32x16_bf16 v[32:47], v[192:195], v[184:187], v[32:47]
	ds_read_b64_tr_b16 v[184:185], v246 offset:9728
	ds_read_b64_tr_b16 v[186:187], v246 offset:11776
	v_fmamk_f32 v157, v157, 0x3dd53b94, v69
	v_exp_f32_e32 v149, v149
	v_fmamk_f32 v158, v158, 0x3dd53b94, v69
	v_exp_f32_e32 v150, v150
	s_waitcnt lgkmcnt(6)
	v_mfma_f32_32x32x16_bf16 v[32:47], v[196:199], v[210:213], v[32:47]
	ds_read_b64_tr_b16 v[210:211], v246 offset:13824
	ds_read_b64_tr_b16 v[212:213], v246 offset:15872
	v_fmamk_f32 v159, v159, 0x3dd53b94, v69
	v_exp_f32_e32 v151, v151
	v_fmamk_f32 v128, v128, 0x3dd53b94, v69
	v_fmamk_f32 v129, v129, 0x3dd53b94, v69
	v_add_u32_e32 v70, s14, v174
	s_waitcnt vmcnt(3)
	ds_write_b128 v70, v[84:87]
	v_mfma_f32_32x32x16_bf16 v[32:47], v[200:203], v[214:217], v[32:47]
	v_exp_f32_e32 v152, v152
	v_fmamk_f32 v130, v130, 0x3dd53b94, v69
	v_fmamk_f32 v131, v131, 0x3dd53b94, v69
	v_exp_f32_e32 v153, v153
	v_add_u32_e32 v71, s14, v175
	s_waitcnt vmcnt(1)
	ds_write_b128 v71, v[92:95]
	s_waitcnt lgkmcnt(6)
	v_mfma_f32_32x32x16_bf16 v[16:31], v[188:191], v[218:221], v[16:31]
	v_fmamk_f32 v132, v132, 0x3dd53b94, v69
	v_fmamk_f32 v133, v133, 0x3dd53b94, v69
	v_exp_f32_e32 v154, v154
	v_fmamk_f32 v134, v134, 0x3dd53b94, v69
	v_fmamk_f32 v135, v135, 0x3dd53b94, v69
	v_add_u32_e32 v70, s15, v179
	ds_write_b128 v70, v[80:83] offset:49152
	ds_write_b128 v70, v[88:91] offset:61440
	v_mfma_f32_32x32x16_bf16 v[16:31], v[192:195], v[222:225], v[16:31]
	v_exp_f32_e32 v155, v155
	v_fmamk_f32 v136, v136, 0x3dd53b94, v69
	v_fmamk_f32 v137, v137, 0x3dd53b94, v69
	v_exp_f32_e32 v156, v156
	v_add_u32_e32 v71, s15, v180
	s_waitcnt vmcnt(0)
	ds_write_b128 v71, v[204:207] offset:49152
	s_waitcnt lgkmcnt(5)
	v_mfma_f32_32x32x16_bf16 v[16:31], v[196:199], v[184:187], v[16:31]
	v_fmamk_f32 v138, v138, 0x3dd53b94, v69
	v_fmamk_f32 v139, v139, 0x3dd53b94, v69
	v_exp_f32_e32 v157, v157
	v_fmamk_f32 v140, v140, 0x3dd53b94, v69
	v_fmamk_f32 v141, v141, 0x3dd53b94, v69
	v_mfma_f32_32x32x16_bf16 v[16:31], v[200:203], v[210:213], v[16:31]
	v_exp_f32_e32 v158, v158
	v_fmamk_f32 v142, v142, 0x3dd53b94, v69
	v_fmamk_f32 v143, v143, 0x3dd53b94, v69
	v_exp_f32_e32 v159, v159
	s_cbranch_vccz .Lattn_skip1
	s_and_saveexec_b64 s[12:13], s[4:5]
	ds_write_b32 v169, v249 offset:128
	s_or_b64 exec, exec, s[12:13]
	s_waitcnt lgkmcnt(0)
	v_add_u32_e32 v250, v168, v208
	ds_read_b128 v[64:67], v250 offset:128
	ds_read_b128 v[68:71], v250 offset:160
	ds_read_b128 v[72:75], v250 offset:192
	ds_read_b128 v[76:79], v250 offset:224
	s_waitcnt lgkmcnt(0)
	v_pk_mul_f32 v[0:1], v[0:1], v[64:65]
	v_pk_mul_f32 v[2:3], v[2:3], v[66:67]
	v_pk_mul_f32 v[4:5], v[4:5], v[68:69]
	v_pk_mul_f32 v[6:7], v[6:7], v[70:71]
	v_pk_mul_f32 v[8:9], v[8:9], v[72:73]
	v_pk_mul_f32 v[10:11], v[10:11], v[74:75]
	v_pk_mul_f32 v[12:13], v[12:13], v[76:77]
	v_pk_mul_f32 v[14:15], v[14:15], v[78:79]
	v_pk_mul_f32 v[48:49], v[48:49], v[64:65]
	v_pk_mul_f32 v[50:51], v[50:51], v[66:67]
	v_pk_mul_f32 v[52:53], v[52:53], v[68:69]
	v_pk_mul_f32 v[54:55], v[54:55], v[70:71]
	v_pk_mul_f32 v[56:57], v[56:57], v[72:73]
	v_pk_mul_f32 v[58:59], v[58:59], v[74:75]
	v_pk_mul_f32 v[60:61], v[60:61], v[76:77]
	v_pk_mul_f32 v[62:63], v[62:63], v[78:79]
	v_pk_mul_f32 v[32:33], v[32:33], v[64:65]
	v_pk_mul_f32 v[34:35], v[34:35], v[66:67]
	v_pk_mul_f32 v[36:37], v[36:37], v[68:69]
	v_pk_mul_f32 v[38:39], v[38:39], v[70:71]
	v_pk_mul_f32 v[40:41], v[40:41], v[72:73]
	v_pk_mul_f32 v[42:43], v[42:43], v[74:75]
	v_pk_mul_f32 v[44:45], v[44:45], v[76:77]
	v_pk_mul_f32 v[46:47], v[46:47], v[78:79]
	v_pk_mul_f32 v[16:17], v[16:17], v[64:65]
	v_pk_mul_f32 v[18:19], v[18:19], v[66:67]
	v_pk_mul_f32 v[20:21], v[20:21], v[68:69]
	v_pk_mul_f32 v[22:23], v[22:23], v[70:71]
	v_pk_mul_f32 v[24:25], v[24:25], v[72:73]
	v_pk_mul_f32 v[26:27], v[26:27], v[74:75]
	v_pk_mul_f32 v[28:29], v[28:29], v[76:77]
	v_pk_mul_f32 v[30:31], v[30:31], v[78:79]

; #define SBAR() __builtin_amdgcn_sched_barrier(0)
; __device__ __forceinline__ void attn_unit(const bf16* __restrict__ Qb, const bf16* __restrict__ KN, const bf16* __restrict__ KR, ...
;     ...
;   }
;   SBAR(); qkt(pB0, pB1, K_lds + rc * SHM_K, qr, qs, kb);
;   finishSM(pA0, pA1, alA, l_reg, pa0, pa1, pa2, pa3); SBAR();
;   pv_d0(o, vb0 + rp * SHM_V, pa0, pa1, pa2, pa3); partialSM(pB0, pB1, m_reg, mnB, alB);
.Lattn_exit:
	v_mov_b32_e32 v149, v80
	v_mov_b32_e32 v150, v81
	v_mov_b32_e32 v151, v82
	v_mov_b32_e32 v157, v83
	v_mov_b32_e32 v159, v84
	v_mov_b32_e32 v188, v85
	v_mov_b32_e32 v152, v86
	v_mov_b32_e32 v158, v87
	v_mov_b32_e32 v144, v88
	v_mov_b32_e32 v146, v89
	v_mov_b32_e32 v153, v90
	v_mov_b32_e32 v154, v91
	v_mov_b32_e32 v145, v92
	v_mov_b32_e32 v147, v93
	v_mov_b32_e32 v155, v94
	v_mov_b32_e32 v156, v95
	v_mov_b32_e32 v142, v64
	v_mov_b32_e32 v143, v65
	v_mov_b32_e32 v140, v66
	v_mov_b32_e32 v141, v67
	v_mov_b32_e32 v138, v68
	v_mov_b32_e32 v139, v69
	v_mov_b32_e32 v136, v70
	v_mov_b32_e32 v137, v71
	v_mov_b32_e32 v134, v72
	v_mov_b32_e32 v135, v73
	v_mov_b32_e32 v132, v74
	v_mov_b32_e32 v133, v75
	v_mov_b32_e32 v130, v76
	v_mov_b32_e32 v131, v77
	v_mov_b32_e32 v128, v78
	v_mov_b32_e32 v129, v79
	v_mov_b32_e32 v148, v249
	s_lshl_b32 s14, s9, 14
	s_mul_i32 s0, s8, 0x6000
	v_lshl_add_u32 v172, s8, 14, v171
	s_setprio 0
